# final RMSNorm fused into the last down-projection epilogue (16-wave rendezvous per half-strip via device-scope atomics); last grid barrier and final pass skipped on the 256-workgroup grid
# speedup vs baseline: 1.0133x; 1.0133x over previous
; __device__ __forceinline__ unsigned cvt_pk_bf16(float lo, float hi) { unsigned r; asm volatile("v_cvt_pk_bf16_f32 %0, %1, %2" : "=v"(r) : "v"(lo), "v"(hi)); return r; }
; __device__ __forceinline__ float bf_lo(unsigned w) { return __uint_as_float(w << 16); }
; __device__ __forceinline__ float bf_hi(unsigned w) { return __uint_as_float(w & 0xffff0000u); }
;     __device__ __forceinline__ void operator()(const Acc& acc, const Unit& u, int wr, int wc, int fr, int fq, LAS unsigned char* lds, f32x4 epar) const {
;         u32x4 hv[2][4][2];
; #pragma unroll
;         for (int ai = 0; ai < 2; ++ai)
; #pragma unroll
;             for (int m = 0; m < 4; ++m) { const int r = u.pm * BM + ai * HALF + wr * 64 + m * 16 + fr;
; #pragma unroll
;                 for (int bj = 0; bj < 2; ++bj) hv[ai][m][bj] = *(const u32x4*)(HB + (size_t)r * DM + u.pn * 256 + bj * 128 + wc * 32 + 8 * fq); }
; #pragma unroll
;         for (int ai = 0; ai < 2; ++ai)
; #pragma unroll
;             for (int m = 0; m < 4; ++m) { const int r = u.pm * BM + ai * HALF + wr * 64 + m * 16 + fr; float s = 0.f;
; #pragma unroll
;                 for (int bj = 0; bj < 2; ++bj) { const size_t off = (size_t)r * DM + u.pn * 256 + bj * 128 + wc * 32 + 8 * fq;
;                     const u32x4 q = hv[ai][m][bj];
;                     f32x4 v0 = (f32x4){bf_lo(q.x), bf_hi(q.x), bf_lo(q.y), bf_hi(q.y)}, v1 = (f32x4){bf_lo(q.z), bf_hi(q.z), bf_lo(q.w), bf_hi(q.w)};
;                     v0 += acc[ai][bj][m][0]; v1 += acc[ai][bj][m][1];
;                     u32x4 w; w.x = cvt_pk_bf16(v0[0], v0[1]); w.y = cvt_pk_bf16(v0[2], v0[3]); w.z = cvt_pk_bf16(v1[0], v1[1]); w.w = cvt_pk_bf16(v1[2], v1[3]);
;                     *(u32x4*)(HB + off) = w;
;                     s += (v0[0] * v0[0] + v0[1] * v0[1]) + (v0[2] * v0[2] + v0[3] * v0[3]) + (v1[0] * v1[0] + v1[1] * v1[1]) + (v1[2] * v1[2] + v1[3] * v1[3]); }
;                 s += __shfl_xor(s, 16); s += __shfl_xor(s, 32);
;                 if (fq == 0) unsafeAtomicAdd(ssq + r, s); }
.LBB0_1067:
	s_cmp_lg_u32 s34, 0x100
	s_cbranch_scc1 .Ldn1_epi_generic
	v_readlane_b32 s98, v252, 50
	v_readlane_b32 s99, v252, 51
	v_readlane_b32 s100, v252, 12
	v_readlane_b32 s101, v252, 13
	v_lshl_add_u32 v216, s78, 8, v226
	s_lshl_b32 s8, s77, 9
	v_lshlrev_b32_e32 v217, 11, v216
	v_mov_b32_e32 v219, 0
	v_add_u32_e32 v217, s8, v217
	v_add_u32_e32 v242, 0x0, v217
	v_mov_b32_e32 v243, 0
	v_lshl_add_u64 v[246:247], v[242:243], 0, v[186:187]
	global_load_dwordx4 v[234:237], v[246:247], off
	global_load_dwordx4 v[238:241], v[246:247], off offset:256
	v_add_u32_e32 v242, 0x8000, v217
	v_mov_b32_e32 v243, 0
	v_lshl_add_u64 v[246:247], v[242:243], 0, v[186:187]
	global_load_dwordx4 v[180:183], v[246:247], off
	global_load_dwordx4 v[176:179], v[246:247], off offset:256
	v_add_u32_e32 v242, 0x10000, v217
	v_mov_b32_e32 v243, 0
	v_lshl_add_u64 v[246:247], v[242:243], 0, v[186:187]
	global_load_dwordx4 v[172:175], v[246:247], off
	global_load_dwordx4 v[168:171], v[246:247], off offset:256
	v_add_u32_e32 v242, 0x18000, v217
	v_mov_b32_e32 v243, 0
	v_lshl_add_u64 v[246:247], v[242:243], 0, v[186:187]
	global_load_dwordx4 v[164:167], v[246:247], off
	global_load_dwordx4 v[160:163], v[246:247], off offset:256
	v_add_u32_e32 v242, 0x40000, v217
	v_mov_b32_e32 v243, 0
	v_lshl_add_u64 v[246:247], v[242:243], 0, v[186:187]
	global_load_dwordx4 v[156:159], v[246:247], off
	global_load_dwordx4 v[152:155], v[246:247], off offset:256
	v_add_u32_e32 v242, 0x48000, v217
	v_mov_b32_e32 v243, 0
	v_lshl_add_u64 v[246:247], v[242:243], 0, v[186:187]
	global_load_dwordx4 v[148:151], v[246:247], off
	global_load_dwordx4 v[144:147], v[246:247], off offset:256
	v_add_u32_e32 v242, 0x50000, v217
	v_mov_b32_e32 v243, 0
	v_lshl_add_u64 v[246:247], v[242:243], 0, v[186:187]
	global_load_dwordx4 v[140:143], v[246:247], off
	global_load_dwordx4 v[136:139], v[246:247], off offset:256
	v_add_u32_e32 v242, 0x58000, v217
	v_mov_b32_e32 v243, 0
	v_lshl_add_u64 v[246:247], v[242:243], 0, v[186:187]
	global_load_dwordx4 v[132:135], v[246:247], off
	global_load_dwordx4 v[128:131], v[246:247], off offset:256
	v_lshlrev_b32_e32 v248, 2, v216
	s_waitcnt vmcnt(14)
	v_lshlrev_b32_e32 v242, 16, v234
	v_and_b32_e32 v243, 0xffff0000, v234
	v_add_f32_e32 v120, v120, v242
	v_add_f32_e32 v121, v121, v243
	v_lshlrev_b32_e32 v244, 16, v235
	v_and_b32_e32 v245, 0xffff0000, v235
	v_add_f32_e32 v122, v122, v244
	v_add_f32_e32 v123, v123, v245
	v_lshlrev_b32_e32 v242, 16, v236
	v_and_b32_e32 v243, 0xffff0000, v236
	v_add_f32_e32 v124, v124, v242
	v_add_f32_e32 v125, v125, v243
	v_lshlrev_b32_e32 v244, 16, v237
	v_and_b32_e32 v245, 0xffff0000, v237
	v_add_f32_e32 v126, v126, v244
	v_add_f32_e32 v127, v127, v245
	v_lshlrev_b32_e32 v242, 16, v238
	v_and_b32_e32 v243, 0xffff0000, v238
	v_add_f32_e32 v116, v116, v242
	v_add_f32_e32 v117, v117, v243
	v_lshlrev_b32_e32 v244, 16, v239
	v_and_b32_e32 v245, 0xffff0000, v239
	v_add_f32_e32 v118, v118, v244
	v_add_f32_e32 v119, v119, v245
	v_lshlrev_b32_e32 v242, 16, v240
	v_and_b32_e32 v243, 0xffff0000, v240
	v_add_f32_e32 v112, v112, v242
	v_add_f32_e32 v113, v113, v243
	v_lshlrev_b32_e32 v244, 16, v241
	v_and_b32_e32 v245, 0xffff0000, v241
	v_add_f32_e32 v114, v114, v244
	v_add_f32_e32 v115, v115, v245
	v_mul_f32_e32 v234, v120, v120
	v_mul_f32_e32 v235, v121, v121
	v_mul_f32_e32 v236, v122, v122
	v_mul_f32_e32 v237, v123, v123
	v_fmac_f32_e32 v234, v124, v124
	v_fmac_f32_e32 v235, v125, v125
	v_fmac_f32_e32 v236, v126, v126
	v_fmac_f32_e32 v237, v127, v127
	v_fmac_f32_e32 v234, v116, v116
	v_fmac_f32_e32 v235, v117, v117
	v_fmac_f32_e32 v236, v118, v118
	v_fmac_f32_e32 v237, v119, v119
	v_fmac_f32_e32 v234, v112, v112
	v_fmac_f32_e32 v235, v113, v113
	v_fmac_f32_e32 v236, v114, v114
	v_fmac_f32_e32 v237, v115, v115
	v_add_f32_e32 v234, v234, v235
	v_add_f32_e32 v236, v236, v237
	v_add_u32_e32 v246, 0x0, v248
	v_add_f32_e32 v208, v234, v236
	s_nop 0
	v_mov_b32_e32 v234, v208
	s_nop 1
	v_permlane16_swap_b32_e32 v208, v234
	v_add_f32_e32 v208, v208, v234
	v_mov_b32_e32 v234, v208
	s_nop 1
	v_permlane32_swap_b32_e32 v208, v234
	v_add_f32_e32 v208, v208, v234
	s_and_b64 exec, exec, s[4:5]
	global_atomic_add_f32 v234, v246, v208, s[12:13] sc0
	s_mov_b64 exec, -1
	s_waitcnt vmcnt(13)
	v_lshlrev_b32_e32 v242, 16, v180
	v_and_b32_e32 v243, 0xffff0000, v180
	v_add_f32_e32 v108, v108, v242
	v_add_f32_e32 v109, v109, v243
	v_lshlrev_b32_e32 v244, 16, v181
	v_and_b32_e32 v245, 0xffff0000, v181
	v_add_f32_e32 v110, v110, v244
	v_add_f32_e32 v111, v111, v245
	v_lshlrev_b32_e32 v242, 16, v182
	v_and_b32_e32 v243, 0xffff0000, v182
	v_add_f32_e32 v104, v104, v242
	v_add_f32_e32 v105, v105, v243
	v_lshlrev_b32_e32 v244, 16, v183
	v_and_b32_e32 v245, 0xffff0000, v183
	v_add_f32_e32 v106, v106, v244
	v_add_f32_e32 v107, v107, v245
	v_lshlrev_b32_e32 v242, 16, v176
	v_and_b32_e32 v243, 0xffff0000, v176
	v_add_f32_e32 v100, v100, v242
	v_add_f32_e32 v101, v101, v243
	v_lshlrev_b32_e32 v244, 16, v177
	v_and_b32_e32 v245, 0xffff0000, v177
	v_add_f32_e32 v102, v102, v244
	v_add_f32_e32 v103, v103, v245
	v_lshlrev_b32_e32 v242, 16, v178
	v_and_b32_e32 v243, 0xffff0000, v178
	v_add_f32_e32 v96, v96, v242
	v_add_f32_e32 v97, v97, v243
	v_lshlrev_b32_e32 v244, 16, v179
	v_and_b32_e32 v245, 0xffff0000, v179
	v_add_f32_e32 v98, v98, v244
	v_add_f32_e32 v99, v99, v245
	v_mul_f32_e32 v180, v108, v108
	v_mul_f32_e32 v181, v109, v109
	v_mul_f32_e32 v182, v110, v110
	v_mul_f32_e32 v183, v111, v111
	v_fmac_f32_e32 v180, v104, v104
	v_fmac_f32_e32 v181, v105, v105
	v_fmac_f32_e32 v182, v106, v106
	v_fmac_f32_e32 v183, v107, v107
	v_fmac_f32_e32 v180, v100, v100
	v_fmac_f32_e32 v181, v101, v101
	v_fmac_f32_e32 v182, v102, v102
	v_fmac_f32_e32 v183, v103, v103
	v_fmac_f32_e32 v180, v96, v96
	v_fmac_f32_e32 v181, v97, v97
	v_fmac_f32_e32 v182, v98, v98
	v_fmac_f32_e32 v183, v99, v99
	v_add_f32_e32 v180, v180, v181
	v_add_f32_e32 v182, v182, v183
	v_add_u32_e32 v246, 0x40, v248
	v_add_f32_e32 v209, v180, v182
	s_nop 0
	v_mov_b32_e32 v235, v209
	s_nop 1
	v_permlane16_swap_b32_e32 v209, v235
	v_add_f32_e32 v209, v209, v235
	v_mov_b32_e32 v235, v209
	s_nop 1
	v_permlane32_swap_b32_e32 v209, v235
	v_add_f32_e32 v209, v209, v235
	s_and_b64 exec, exec, s[4:5]
	global_atomic_add_f32 v235, v246, v209, s[12:13] sc0
	s_mov_b64 exec, -1
	s_waitcnt vmcnt(12)
; __device__ __forceinline__ unsigned cvt_pk_bf16(float lo, float hi) { unsigned r; asm volatile("v_cvt_pk_bf16_f32 %0, %1, %2" : "=v"(r) : "v"(lo), "v"(hi)); return r; }
; __device__ __forceinline__ float bf_lo(unsigned w) { return __uint_as_float(w << 16); }
; __device__ __forceinline__ float bf_hi(unsigned w) { return __uint_as_float(w & 0xffff0000u); }
;     __device__ __forceinline__ void operator()(const Acc& acc, const Unit& u, int wr, int wc, int fr, int fq, LAS unsigned char* lds, f32x4 epar) const {
;     ...
;         for (int ai = 0; ai < 2; ++ai)
; #pragma unroll
;             for (int m = 0; m < 4; ++m) { const int r = u.pm * BM + ai * HALF + wr * 64 + m * 16 + fr; float s = 0.f;
; #pragma unroll
;                 for (int bj = 0; bj < 2; ++bj) { const size_t off = (size_t)r * DM + u.pn * 256 + bj * 128 + wc * 32 + 8 * fq;
;                     const u32x4 q = hv[ai][m][bj];
;                     f32x4 v0 = (f32x4){bf_lo(q.x), bf_hi(q.x), bf_lo(q.y), bf_hi(q.y)}, v1 = (f32x4){bf_lo(q.z), bf_hi(q.z), bf_lo(q.w), bf_hi(q.w)};
;                     v0 += acc[ai][bj][m][0]; v1 += acc[ai][bj][m][1];
;                     u32x4 w; w.x = cvt_pk_bf16(v0[0], v0[1]); w.y = cvt_pk_bf16(v0[2], v0[3]); w.z = cvt_pk_bf16(v1[0], v1[1]); w.w = cvt_pk_bf16(v1[2], v1[3]);
;                     *(u32x4*)(HB + off) = w;
;                     s += (v0[0] * v0[0] + v0[1] * v0[1]) + (v0[2] * v0[2] + v0[3] * v0[3]) + (v1[0] * v1[0] + v1[1] * v1[1]) + (v1[2] * v1[2] + v1[3] * v1[3]); }
;                 s += __shfl_xor(s, 16); s += __shfl_xor(s, 32);
;                 if (fq == 0) unsafeAtomicAdd(ssq + r, s); }
	v_lshlrev_b32_e32 v242, 16, v172
	v_and_b32_e32 v243, 0xffff0000, v172
	v_add_f32_e32 v92, v92, v242
	v_add_f32_e32 v93, v93, v243
	v_lshlrev_b32_e32 v244, 16, v173
	v_and_b32_e32 v245, 0xffff0000, v173
	v_add_f32_e32 v94, v94, v244
	v_add_f32_e32 v95, v95, v245
	v_lshlrev_b32_e32 v242, 16, v174
	v_and_b32_e32 v243, 0xffff0000, v174
	v_add_f32_e32 v88, v88, v242
	v_add_f32_e32 v89, v89, v243
	v_lshlrev_b32_e32 v244, 16, v175
	v_and_b32_e32 v245, 0xffff0000, v175
	v_add_f32_e32 v90, v90, v244
	v_add_f32_e32 v91, v91, v245
	v_lshlrev_b32_e32 v242, 16, v168
	v_and_b32_e32 v243, 0xffff0000, v168
	v_add_f32_e32 v84, v84, v242
	v_add_f32_e32 v85, v85, v243
	v_lshlrev_b32_e32 v244, 16, v169
	v_and_b32_e32 v245, 0xffff0000, v169
	v_add_f32_e32 v86, v86, v244
	v_add_f32_e32 v87, v87, v245
	v_lshlrev_b32_e32 v242, 16, v170
	v_and_b32_e32 v243, 0xffff0000, v170
	v_add_f32_e32 v80, v80, v242
	v_add_f32_e32 v81, v81, v243
	v_lshlrev_b32_e32 v244, 16, v171
	v_and_b32_e32 v245, 0xffff0000, v171
	v_add_f32_e32 v82, v82, v244
	v_add_f32_e32 v83, v83, v245
	v_mul_f32_e32 v172, v92, v92
	v_mul_f32_e32 v173, v93, v93
	v_mul_f32_e32 v174, v94, v94
	v_mul_f32_e32 v175, v95, v95
	v_fmac_f32_e32 v172, v88, v88
	v_fmac_f32_e32 v173, v89, v89
	v_fmac_f32_e32 v174, v90, v90
	v_fmac_f32_e32 v175, v91, v91
	v_fmac_f32_e32 v172, v84, v84
	v_fmac_f32_e32 v173, v85, v85
	v_fmac_f32_e32 v174, v86, v86
	v_fmac_f32_e32 v175, v87, v87
	v_fmac_f32_e32 v172, v80, v80
	v_fmac_f32_e32 v173, v81, v81
	v_fmac_f32_e32 v174, v82, v82
	v_fmac_f32_e32 v175, v83, v83
	v_add_f32_e32 v172, v172, v173
	v_add_f32_e32 v174, v174, v175
	v_add_u32_e32 v246, 0x80, v248
	v_add_f32_e32 v210, v172, v174
	s_nop 0
	v_mov_b32_e32 v236, v210
	s_nop 1
	v_permlane16_swap_b32_e32 v210, v236
	v_add_f32_e32 v210, v210, v236
	v_mov_b32_e32 v236, v210
	s_nop 1
	v_permlane32_swap_b32_e32 v210, v236
	v_add_f32_e32 v210, v210, v236
	s_and_b64 exec, exec, s[4:5]
	global_atomic_add_f32 v236, v246, v210, s[12:13] sc0
	s_mov_b64 exec, -1
	s_waitcnt vmcnt(11)
	v_lshlrev_b32_e32 v242, 16, v164
	v_and_b32_e32 v243, 0xffff0000, v164
	v_add_f32_e32 v76, v76, v242
	v_add_f32_e32 v77, v77, v243
	v_lshlrev_b32_e32 v244, 16, v165
	v_and_b32_e32 v245, 0xffff0000, v165
	v_add_f32_e32 v78, v78, v244
	v_add_f32_e32 v79, v79, v245
	v_lshlrev_b32_e32 v242, 16, v166
	v_and_b32_e32 v243, 0xffff0000, v166
	v_add_f32_e32 v72, v72, v242
	v_add_f32_e32 v73, v73, v243
	v_lshlrev_b32_e32 v244, 16, v167
	v_and_b32_e32 v245, 0xffff0000, v167
	v_add_f32_e32 v74, v74, v244
	v_add_f32_e32 v75, v75, v245
	v_lshlrev_b32_e32 v242, 16, v160
	v_and_b32_e32 v243, 0xffff0000, v160
	v_add_f32_e32 v68, v68, v242
	v_add_f32_e32 v69, v69, v243
	v_lshlrev_b32_e32 v244, 16, v161
	v_and_b32_e32 v245, 0xffff0000, v161
	v_add_f32_e32 v70, v70, v244
	v_add_f32_e32 v71, v71, v245
	v_lshlrev_b32_e32 v242, 16, v162
	v_and_b32_e32 v243, 0xffff0000, v162
	v_add_f32_e32 v64, v64, v242
	v_add_f32_e32 v65, v65, v243
	v_lshlrev_b32_e32 v244, 16, v163
	v_and_b32_e32 v245, 0xffff0000, v163
	v_add_f32_e32 v66, v66, v244
	v_add_f32_e32 v67, v67, v245
	v_mul_f32_e32 v164, v76, v76
	v_mul_f32_e32 v165, v77, v77
	v_mul_f32_e32 v166, v78, v78
	v_mul_f32_e32 v167, v79, v79
	v_fmac_f32_e32 v164, v72, v72
	v_fmac_f32_e32 v165, v73, v73
	v_fmac_f32_e32 v166, v74, v74
	v_fmac_f32_e32 v167, v75, v75
	v_fmac_f32_e32 v164, v68, v68
	v_fmac_f32_e32 v165, v69, v69
	v_fmac_f32_e32 v166, v70, v70
	v_fmac_f32_e32 v167, v71, v71
	v_fmac_f32_e32 v164, v64, v64
	v_fmac_f32_e32 v165, v65, v65
	v_fmac_f32_e32 v166, v66, v66
	v_fmac_f32_e32 v167, v67, v67
	v_add_f32_e32 v164, v164, v165
	v_add_f32_e32 v166, v166, v167
	v_add_u32_e32 v246, 0xc0, v248
	v_add_f32_e32 v211, v164, v166
	s_nop 0
	v_mov_b32_e32 v237, v211
	s_nop 1
	v_permlane16_swap_b32_e32 v211, v237
	v_add_f32_e32 v211, v211, v237
	v_mov_b32_e32 v237, v211
	s_nop 1
	v_permlane32_swap_b32_e32 v211, v237
	v_add_f32_e32 v211, v211, v237
	s_and_b64 exec, exec, s[4:5]
	global_atomic_add_f32 v237, v246, v211, s[12:13] sc0
	s_mov_b64 exec, -1
	s_waitcnt vmcnt(10)
	v_lshlrev_b32_e32 v242, 16, v156
	v_and_b32_e32 v243, 0xffff0000, v156
	v_add_f32_e32 v60, v60, v242
	v_add_f32_e32 v61, v61, v243
	v_lshlrev_b32_e32 v244, 16, v157
	v_and_b32_e32 v245, 0xffff0000, v157
	v_add_f32_e32 v62, v62, v244
	v_add_f32_e32 v63, v63, v245
	v_lshlrev_b32_e32 v242, 16, v158
	v_and_b32_e32 v243, 0xffff0000, v158
	v_add_f32_e32 v56, v56, v242
	v_add_f32_e32 v57, v57, v243
	v_lshlrev_b32_e32 v244, 16, v159
	v_and_b32_e32 v245, 0xffff0000, v159
	v_add_f32_e32 v58, v58, v244
	v_add_f32_e32 v59, v59, v245
	v_lshlrev_b32_e32 v242, 16, v152
	v_and_b32_e32 v243, 0xffff0000, v152
	v_add_f32_e32 v52, v52, v242
	v_add_f32_e32 v53, v53, v243
	v_lshlrev_b32_e32 v244, 16, v153
	v_and_b32_e32 v245, 0xffff0000, v153
	v_add_f32_e32 v54, v54, v244
	v_add_f32_e32 v55, v55, v245
	v_lshlrev_b32_e32 v242, 16, v154
	v_and_b32_e32 v243, 0xffff0000, v154
	v_add_f32_e32 v48, v48, v242
	v_add_f32_e32 v49, v49, v243
	v_lshlrev_b32_e32 v244, 16, v155
	v_and_b32_e32 v245, 0xffff0000, v155
	v_add_f32_e32 v50, v50, v244
	v_add_f32_e32 v51, v51, v245
	v_mul_f32_e32 v156, v60, v60
	v_mul_f32_e32 v157, v61, v61
	v_mul_f32_e32 v158, v62, v62
	v_mul_f32_e32 v159, v63, v63
	v_fmac_f32_e32 v156, v56, v56
	v_fmac_f32_e32 v157, v57, v57
	v_fmac_f32_e32 v158, v58, v58
	v_fmac_f32_e32 v159, v59, v59
	v_fmac_f32_e32 v156, v52, v52
	v_fmac_f32_e32 v157, v53, v53
	v_fmac_f32_e32 v158, v54, v54
	v_fmac_f32_e32 v159, v55, v55
	v_fmac_f32_e32 v156, v48, v48
	v_fmac_f32_e32 v157, v49, v49
	v_fmac_f32_e32 v158, v50, v50
	v_fmac_f32_e32 v159, v51, v51
	v_add_f32_e32 v156, v156, v157
	v_add_f32_e32 v158, v158, v159
	v_add_u32_e32 v246, 0x200, v248
	v_add_f32_e32 v212, v156, v158
	s_nop 0
	v_mov_b32_e32 v238, v212
	s_nop 1
	v_permlane16_swap_b32_e32 v212, v238
	v_add_f32_e32 v212, v212, v238
	v_mov_b32_e32 v238, v212
	s_nop 1
	v_permlane32_swap_b32_e32 v212, v238
	v_add_f32_e32 v212, v212, v238
	s_and_b64 exec, exec, s[4:5]
	global_atomic_add_f32 v238, v246, v212, s[12:13] sc0
	s_mov_b64 exec, -1
	s_waitcnt vmcnt(9)
; __device__ __forceinline__ unsigned cvt_pk_bf16(float lo, float hi) { unsigned r; asm volatile("v_cvt_pk_bf16_f32 %0, %1, %2" : "=v"(r) : "v"(lo), "v"(hi)); return r; }
; __device__ __forceinline__ float bf_lo(unsigned w) { return __uint_as_float(w << 16); }
; __device__ __forceinline__ float bf_hi(unsigned w) { return __uint_as_float(w & 0xffff0000u); }
;     __device__ __forceinline__ void operator()(const Acc& acc, const Unit& u, int wr, int wc, int fr, int fq, LAS unsigned char* lds, f32x4 epar) const {
;     ...
;         for (int ai = 0; ai < 2; ++ai)
; #pragma unroll
;             for (int m = 0; m < 4; ++m) { const int r = u.pm * BM + ai * HALF + wr * 64 + m * 16 + fr; float s = 0.f;
; #pragma unroll
;                 for (int bj = 0; bj < 2; ++bj) { const size_t off = (size_t)r * DM + u.pn * 256 + bj * 128 + wc * 32 + 8 * fq;
;                     const u32x4 q = hv[ai][m][bj];
;                     f32x4 v0 = (f32x4){bf_lo(q.x), bf_hi(q.x), bf_lo(q.y), bf_hi(q.y)}, v1 = (f32x4){bf_lo(q.z), bf_hi(q.z), bf_lo(q.w), bf_hi(q.w)};
;                     v0 += acc[ai][bj][m][0]; v1 += acc[ai][bj][m][1];
;                     u32x4 w; w.x = cvt_pk_bf16(v0[0], v0[1]); w.y = cvt_pk_bf16(v0[2], v0[3]); w.z = cvt_pk_bf16(v1[0], v1[1]); w.w = cvt_pk_bf16(v1[2], v1[3]);
;                     *(u32x4*)(HB + off) = w;
;                     s += (v0[0] * v0[0] + v0[1] * v0[1]) + (v0[2] * v0[2] + v0[3] * v0[3]) + (v1[0] * v1[0] + v1[1] * v1[1]) + (v1[2] * v1[2] + v1[3] * v1[3]); }
;                 s += __shfl_xor(s, 16); s += __shfl_xor(s, 32);
;                 if (fq == 0) unsafeAtomicAdd(ssq + r, s); }
	v_lshlrev_b32_e32 v242, 16, v148
	v_and_b32_e32 v243, 0xffff0000, v148
	v_add_f32_e32 v44, v44, v242
	v_add_f32_e32 v45, v45, v243
	v_lshlrev_b32_e32 v244, 16, v149
	v_and_b32_e32 v245, 0xffff0000, v149
	v_add_f32_e32 v46, v46, v244
	v_add_f32_e32 v47, v47, v245
	v_lshlrev_b32_e32 v242, 16, v150
	v_and_b32_e32 v243, 0xffff0000, v150
	v_add_f32_e32 v40, v40, v242
	v_add_f32_e32 v41, v41, v243
	v_lshlrev_b32_e32 v244, 16, v151
	v_and_b32_e32 v245, 0xffff0000, v151
	v_add_f32_e32 v42, v42, v244
	v_add_f32_e32 v43, v43, v245
	v_lshlrev_b32_e32 v242, 16, v144
	v_and_b32_e32 v243, 0xffff0000, v144
	v_add_f32_e32 v36, v36, v242
	v_add_f32_e32 v37, v37, v243
	v_lshlrev_b32_e32 v244, 16, v145
	v_and_b32_e32 v245, 0xffff0000, v145
	v_add_f32_e32 v38, v38, v244
	v_add_f32_e32 v39, v39, v245
	v_lshlrev_b32_e32 v242, 16, v146
	v_and_b32_e32 v243, 0xffff0000, v146
	v_add_f32_e32 v32, v32, v242
	v_add_f32_e32 v33, v33, v243
	v_lshlrev_b32_e32 v244, 16, v147
	v_and_b32_e32 v245, 0xffff0000, v147
	v_add_f32_e32 v34, v34, v244
	v_add_f32_e32 v35, v35, v245
	v_mul_f32_e32 v148, v44, v44
	v_mul_f32_e32 v149, v45, v45
	v_mul_f32_e32 v150, v46, v46
	v_mul_f32_e32 v151, v47, v47
	v_fmac_f32_e32 v148, v40, v40
	v_fmac_f32_e32 v149, v41, v41
	v_fmac_f32_e32 v150, v42, v42
	v_fmac_f32_e32 v151, v43, v43
	v_fmac_f32_e32 v148, v36, v36
	v_fmac_f32_e32 v149, v37, v37
	v_fmac_f32_e32 v150, v38, v38
	v_fmac_f32_e32 v151, v39, v39
	v_fmac_f32_e32 v148, v32, v32
	v_fmac_f32_e32 v149, v33, v33
	v_fmac_f32_e32 v150, v34, v34
	v_fmac_f32_e32 v151, v35, v35
	v_add_f32_e32 v148, v148, v149
	v_add_f32_e32 v150, v150, v151
	v_add_u32_e32 v246, 0x240, v248
	v_add_f32_e32 v213, v148, v150
	s_nop 0
	v_mov_b32_e32 v239, v213
	s_nop 1
	v_permlane16_swap_b32_e32 v213, v239
	v_add_f32_e32 v213, v213, v239
	v_mov_b32_e32 v239, v213
	s_nop 1
	v_permlane32_swap_b32_e32 v213, v239
	v_add_f32_e32 v213, v213, v239
	s_and_b64 exec, exec, s[4:5]
	global_atomic_add_f32 v239, v246, v213, s[12:13] sc0
	s_mov_b64 exec, -1
	s_waitcnt vmcnt(8)
	v_lshlrev_b32_e32 v242, 16, v140
	v_and_b32_e32 v243, 0xffff0000, v140
	v_add_f32_e32 v28, v28, v242
	v_add_f32_e32 v29, v29, v243
	v_lshlrev_b32_e32 v244, 16, v141
	v_and_b32_e32 v245, 0xffff0000, v141
	v_add_f32_e32 v30, v30, v244
	v_add_f32_e32 v31, v31, v245
	v_lshlrev_b32_e32 v242, 16, v142
	v_and_b32_e32 v243, 0xffff0000, v142
	v_add_f32_e32 v24, v24, v242
	v_add_f32_e32 v25, v25, v243
	v_lshlrev_b32_e32 v244, 16, v143
	v_and_b32_e32 v245, 0xffff0000, v143
	v_add_f32_e32 v26, v26, v244
	v_add_f32_e32 v27, v27, v245
	v_lshlrev_b32_e32 v242, 16, v136
	v_and_b32_e32 v243, 0xffff0000, v136
	v_add_f32_e32 v20, v20, v242
	v_add_f32_e32 v21, v21, v243
	v_lshlrev_b32_e32 v244, 16, v137
	v_and_b32_e32 v245, 0xffff0000, v137
	v_add_f32_e32 v22, v22, v244
	v_add_f32_e32 v23, v23, v245
	v_lshlrev_b32_e32 v242, 16, v138
	v_and_b32_e32 v243, 0xffff0000, v138
	v_add_f32_e32 v16, v16, v242
	v_add_f32_e32 v17, v17, v243
	v_lshlrev_b32_e32 v244, 16, v139
	v_and_b32_e32 v245, 0xffff0000, v139
	v_add_f32_e32 v18, v18, v244
	v_add_f32_e32 v19, v19, v245
	v_mul_f32_e32 v140, v28, v28
	v_mul_f32_e32 v141, v29, v29
	v_mul_f32_e32 v142, v30, v30
	v_mul_f32_e32 v143, v31, v31
	v_fmac_f32_e32 v140, v24, v24
	v_fmac_f32_e32 v141, v25, v25
	v_fmac_f32_e32 v142, v26, v26
	v_fmac_f32_e32 v143, v27, v27
	v_fmac_f32_e32 v140, v20, v20
	v_fmac_f32_e32 v141, v21, v21
	v_fmac_f32_e32 v142, v22, v22
	v_fmac_f32_e32 v143, v23, v23
	v_fmac_f32_e32 v140, v16, v16
	v_fmac_f32_e32 v141, v17, v17
	v_fmac_f32_e32 v142, v18, v18
	v_fmac_f32_e32 v143, v19, v19
	v_add_f32_e32 v140, v140, v141
	v_add_f32_e32 v142, v142, v143
	v_add_u32_e32 v246, 0x280, v248
	v_add_f32_e32 v214, v140, v142
	s_nop 0
	v_mov_b32_e32 v240, v214
	s_nop 1
	v_permlane16_swap_b32_e32 v214, v240
	v_add_f32_e32 v214, v214, v240
	v_mov_b32_e32 v240, v214
	s_nop 1
	v_permlane32_swap_b32_e32 v214, v240
	v_add_f32_e32 v214, v214, v240
	s_and_b64 exec, exec, s[4:5]
	global_atomic_add_f32 v240, v246, v214, s[12:13] sc0
	s_mov_b64 exec, -1
	s_waitcnt vmcnt(7)
	v_lshlrev_b32_e32 v242, 16, v132
	v_and_b32_e32 v243, 0xffff0000, v132
	v_add_f32_e32 v12, v12, v242
	v_add_f32_e32 v13, v13, v243
	v_lshlrev_b32_e32 v244, 16, v133
	v_and_b32_e32 v245, 0xffff0000, v133
	v_add_f32_e32 v14, v14, v244
	v_add_f32_e32 v15, v15, v245
	v_lshlrev_b32_e32 v242, 16, v134
	v_and_b32_e32 v243, 0xffff0000, v134
	v_add_f32_e32 v8, v8, v242
	v_add_f32_e32 v9, v9, v243
	v_lshlrev_b32_e32 v244, 16, v135
	v_and_b32_e32 v245, 0xffff0000, v135
	v_add_f32_e32 v10, v10, v244
	v_add_f32_e32 v11, v11, v245
	v_lshlrev_b32_e32 v242, 16, v128
	v_and_b32_e32 v243, 0xffff0000, v128
	v_add_f32_e32 v4, v4, v242
	v_add_f32_e32 v5, v5, v243
	v_lshlrev_b32_e32 v244, 16, v129
	v_and_b32_e32 v245, 0xffff0000, v129
	v_add_f32_e32 v6, v6, v244
	v_add_f32_e32 v7, v7, v245
	v_lshlrev_b32_e32 v242, 16, v130
	v_and_b32_e32 v243, 0xffff0000, v130
	v_add_f32_e32 v0, v0, v242
	v_add_f32_e32 v1, v1, v243
	v_lshlrev_b32_e32 v244, 16, v131
	v_and_b32_e32 v245, 0xffff0000, v131
	v_add_f32_e32 v2, v2, v244
	v_add_f32_e32 v3, v3, v245
	v_mul_f32_e32 v132, v12, v12
	v_mul_f32_e32 v133, v13, v13
	v_mul_f32_e32 v134, v14, v14
	v_mul_f32_e32 v135, v15, v15
	v_fmac_f32_e32 v132, v8, v8
	v_fmac_f32_e32 v133, v9, v9
	v_fmac_f32_e32 v134, v10, v10
	v_fmac_f32_e32 v135, v11, v11
	v_fmac_f32_e32 v132, v4, v4
	v_fmac_f32_e32 v133, v5, v5
	v_fmac_f32_e32 v134, v6, v6
	v_fmac_f32_e32 v135, v7, v7
	v_fmac_f32_e32 v132, v0, v0
	v_fmac_f32_e32 v133, v1, v1
	v_fmac_f32_e32 v134, v2, v2
	v_fmac_f32_e32 v135, v3, v3
	v_add_f32_e32 v132, v132, v133
	v_add_f32_e32 v134, v134, v135
	v_add_u32_e32 v246, 0x2c0, v248
	v_add_f32_e32 v215, v132, v134
	s_nop 0
	v_mov_b32_e32 v241, v215
	s_nop 1
	v_permlane16_swap_b32_e32 v215, v241
	v_add_f32_e32 v215, v215, v241
	v_mov_b32_e32 v241, v215
	s_nop 1
	v_permlane32_swap_b32_e32 v215, v241
	v_add_f32_e32 v215, v215, v241
	s_and_b64 exec, exec, s[4:5]
	global_atomic_add_f32 v241, v246, v215, s[12:13] sc0
	s_mov_b64 exec, -1
	v_readfirstlane_b32 s9, v232
	s_lshl_b32 s8, s78, 3
	s_nop 1
	s_lshr_b32 s9, s9, 8
	s_lshl_b32 s9, s9, 2
	s_add_i32 s8, s8, s9
	s_add_i32 s8, s8, 0x3600
	v_mov_b32_e32 v251, s8
	v_mov_b32_e32 v218, 1
	s_waitcnt vmcnt(0)
	s_mov_b64 exec, 1
	global_atomic_add v251, v218, s[62:63]
	s_mov_b64 exec, -1
	s_mov_b32 s8, 0
; __device__ __forceinline__ float bf_lo(unsigned w) { return __uint_as_float(w << 16); }
; __device__ __forceinline__ float bf_hi(unsigned w) { return __uint_as_float(w & 0xffff0000u); }
; __device__ __forceinline__ int otid() { int t = threadIdx.x; asm volatile("" : "+v"(t)); return t; }
; __device__ __forceinline__ void final_phase(float* out, const bf16_t* HB, const float* ssq, const float* gf) {
;     for (int idx = blockIdx.x * 512 + otid(); idx < MTOK * 128; idx += gridDim.x * 512) {
;         const int r = idx >> 7, c = (idx & 127) * 8;
;         const float rs = rsqrtf(ssq[r] * (1.0f / DM) + RMS_EPS);
;         const u32x4 q = __builtin_nontemporal_load((const u32x4*)(HB + (size_t)idx * 8)); const f32x4 g0 = *(const f32x4*)(gf + c), g1 = *(const f32x4*)(gf + c + 4);
;         f32x4 v0 = (f32x4){bf_lo(q.x), bf_hi(q.x), bf_lo(q.y), bf_hi(q.y)}, v1 = (f32x4){bf_lo(q.z), bf_hi(q.z), bf_lo(q.w), bf_hi(q.w)};
;         v0 *= g0 * rs; v1 *= g1 * rs;
;         __builtin_nontemporal_store(v0, (f32x4*)(out + (size_t)idx * 8)); __builtin_nontemporal_store(v1, (f32x4*)(out + (size_t)idx * 8 + 4));
.Ldn1_poll:
	v_mov_b32_e32 v243, 0
	s_mov_b64 exec, 1
	global_atomic_add v242, v251, v243, s[62:63] sc0
	s_mov_b64 exec, -1
	s_waitcnt vmcnt(0)
	v_readfirstlane_b32 s9, v242
	s_add_u32 s8, s8, 1
	s_cmp_ge_u32 s9, 16
	s_cbranch_scc1 .Ldn1_go
	s_sleep 1
	s_cmp_lt_u32 s8, 0x4000
	s_cbranch_scc1 .Ldn1_poll
.Ldn1_go:
	s_and_b64 exec, exec, s[4:5]
	v_add_u32_e32 v246, 0x0, v248
	global_atomic_add_f32 v208, v246, v219, s[12:13] sc0
	v_add_u32_e32 v246, 0x40, v248
	global_atomic_add_f32 v209, v246, v219, s[12:13] sc0
	v_add_u32_e32 v246, 0x80, v248
	global_atomic_add_f32 v210, v246, v219, s[12:13] sc0
	v_add_u32_e32 v246, 0xc0, v248
	global_atomic_add_f32 v211, v246, v219, s[12:13] sc0
	v_add_u32_e32 v246, 0x200, v248
	global_atomic_add_f32 v212, v246, v219, s[12:13] sc0
	v_add_u32_e32 v246, 0x240, v248
	global_atomic_add_f32 v213, v246, v219, s[12:13] sc0
	v_add_u32_e32 v246, 0x280, v248
	global_atomic_add_f32 v214, v246, v219, s[12:13] sc0
	v_add_u32_e32 v246, 0x2c0, v248
	global_atomic_add_f32 v215, v246, v219, s[12:13] sc0
	s_mov_b64 exec, -1
	s_lshl_b32 s9, s77, 10
	v_lshl_add_u32 v249, v184, 1, s9
	v_bfe_u32 v242, v232, 6, 2
	v_lshl_add_u32 v249, v242, 7, v249
	v_lshlrev_b32_e32 v250, 12, v216
	global_load_dwordx4 v[192:195], v249, s[100:101]
	global_load_dwordx4 v[196:199], v249, s[100:101] offset:16
	global_load_dwordx4 v[200:203], v249, s[100:101] offset:512
	global_load_dwordx4 v[204:207], v249, s[100:101] offset:528
	v_add_u32_e32 v250, v250, v249
	v_mov_b32_e32 v245, 0x358637bd
	s_waitcnt vmcnt(0)
	v_mov_b32_e32 v234, v208
	v_mov_b32_e32 v235, v209
	v_mov_b32_e32 v236, v210
	v_mov_b32_e32 v237, v211
	v_mov_b32_e32 v238, v212
	v_mov_b32_e32 v239, v213
	v_mov_b32_e32 v240, v214
	v_mov_b32_e32 v241, v215
	s_nop 1
	v_permlane16_swap_b32_e32 v208, v234
	v_permlane16_swap_b32_e32 v209, v235
	v_permlane16_swap_b32_e32 v210, v236
	v_permlane16_swap_b32_e32 v211, v237
	v_permlane16_swap_b32_e32 v212, v238
	v_permlane16_swap_b32_e32 v213, v239
	v_permlane16_swap_b32_e32 v214, v240
	v_permlane16_swap_b32_e32 v215, v241
	v_mov_b32_e32 v234, v208
	v_mov_b32_e32 v235, v209
	v_mov_b32_e32 v236, v210
	v_mov_b32_e32 v237, v211
	v_mov_b32_e32 v238, v212
	v_mov_b32_e32 v239, v213
	v_mov_b32_e32 v240, v214
	v_mov_b32_e32 v241, v215
	s_nop 1
	v_permlane32_swap_b32_e32 v208, v234
	v_permlane32_swap_b32_e32 v209, v235
	v_permlane32_swap_b32_e32 v210, v236
	v_permlane32_swap_b32_e32 v211, v237
	v_permlane32_swap_b32_e32 v212, v238
	v_permlane32_swap_b32_e32 v213, v239
	v_permlane32_swap_b32_e32 v214, v240
	v_permlane32_swap_b32_e32 v215, v241
	s_nop 1
	v_fmamk_f32 v208, v208, 0x3a800000, v245
	v_fmamk_f32 v209, v209, 0x3a800000, v245
	v_fmamk_f32 v210, v210, 0x3a800000, v245
	v_fmamk_f32 v211, v211, 0x3a800000, v245
	v_fmamk_f32 v212, v212, 0x3a800000, v245
	v_fmamk_f32 v213, v213, 0x3a800000, v245
	v_fmamk_f32 v214, v214, 0x3a800000, v245
	v_fmamk_f32 v215, v215, 0x3a800000, v245
	v_rsq_f32_e32 v208, v208
	v_rsq_f32_e32 v209, v209
	v_rsq_f32_e32 v210, v210
	v_rsq_f32_e32 v211, v211
	v_rsq_f32_e32 v212, v212
	v_rsq_f32_e32 v213, v213
	v_rsq_f32_e32 v214, v214
	v_rsq_f32_e32 v215, v215
	s_nop 0
	v_mul_f32_e32 v234, v192, v208
	v_mul_f32_e32 v235, v193, v208
	v_mul_f32_e32 v236, v194, v208
	v_mul_f32_e32 v237, v195, v208
	v_mul_f32_e32 v238, v196, v208
	v_mul_f32_e32 v239, v197, v208
	v_mul_f32_e32 v240, v198, v208
	v_mul_f32_e32 v241, v199, v208
	v_mul_f32_e32 v120, v120, v234
	v_mul_f32_e32 v121, v121, v235
	v_mul_f32_e32 v122, v122, v236
	v_mul_f32_e32 v123, v123, v237
	v_mul_f32_e32 v124, v124, v238
	v_mul_f32_e32 v125, v125, v239
	v_mul_f32_e32 v126, v126, v240
	v_mul_f32_e32 v127, v127, v241
	v_mul_f32_e32 v234, v200, v208
	v_mul_f32_e32 v235, v201, v208
	v_mul_f32_e32 v236, v202, v208
	v_mul_f32_e32 v237, v203, v208
	v_mul_f32_e32 v238, v204, v208
	v_mul_f32_e32 v239, v205, v208
	v_mul_f32_e32 v240, v206, v208
	v_mul_f32_e32 v241, v207, v208
	v_mul_f32_e32 v116, v116, v234
	v_mul_f32_e32 v117, v117, v235
	v_mul_f32_e32 v118, v118, v236
	v_mul_f32_e32 v119, v119, v237
	v_mul_f32_e32 v112, v112, v238
	v_mul_f32_e32 v113, v113, v239
	v_mul_f32_e32 v114, v114, v240
	v_mul_f32_e32 v115, v115, v241
	v_add_u32_e32 v246, 0x0, v250
	global_store_dwordx4 v246, v[120:123], s[98:99] nt
	global_store_dwordx4 v246, v[124:127], s[98:99] offset:16 nt
	global_store_dwordx4 v246, v[116:119], s[98:99] offset:512 nt
	global_store_dwordx4 v246, v[112:115], s[98:99] offset:528 nt
	v_mul_f32_e32 v234, v192, v209
	v_mul_f32_e32 v235, v193, v209
	v_mul_f32_e32 v236, v194, v209
	v_mul_f32_e32 v237, v195, v209
	v_mul_f32_e32 v238, v196, v209
	v_mul_f32_e32 v239, v197, v209
	v_mul_f32_e32 v240, v198, v209
	v_mul_f32_e32 v241, v199, v209
	v_mul_f32_e32 v108, v108, v234
	v_mul_f32_e32 v109, v109, v235
	v_mul_f32_e32 v110, v110, v236
	v_mul_f32_e32 v111, v111, v237
	v_mul_f32_e32 v104, v104, v238
	v_mul_f32_e32 v105, v105, v239
	v_mul_f32_e32 v106, v106, v240
	v_mul_f32_e32 v107, v107, v241
	v_mul_f32_e32 v234, v200, v209
	v_mul_f32_e32 v235, v201, v209
	v_mul_f32_e32 v236, v202, v209
	v_mul_f32_e32 v237, v203, v209
	v_mul_f32_e32 v238, v204, v209
	v_mul_f32_e32 v239, v205, v209
	v_mul_f32_e32 v240, v206, v209
	v_mul_f32_e32 v241, v207, v209
	v_mul_f32_e32 v100, v100, v234
	v_mul_f32_e32 v101, v101, v235
	v_mul_f32_e32 v102, v102, v236
	v_mul_f32_e32 v103, v103, v237
	v_mul_f32_e32 v96, v96, v238
	v_mul_f32_e32 v97, v97, v239
	v_mul_f32_e32 v98, v98, v240
	v_mul_f32_e32 v99, v99, v241
	v_add_u32_e32 v246, 0x10000, v250
	global_store_dwordx4 v246, v[108:111], s[98:99] nt
	global_store_dwordx4 v246, v[104:107], s[98:99] offset:16 nt
	global_store_dwordx4 v246, v[100:103], s[98:99] offset:512 nt
; __device__ __forceinline__ float bf_lo(unsigned w) { return __uint_as_float(w << 16); }
; __device__ __forceinline__ float bf_hi(unsigned w) { return __uint_as_float(w & 0xffff0000u); }
; __device__ __forceinline__ void final_phase(float* out, const bf16_t* HB, const float* ssq, const float* gf) {
;     ...
;         const float rs = rsqrtf(ssq[r] * (1.0f / DM) + RMS_EPS);
;         const u32x4 q = __builtin_nontemporal_load((const u32x4*)(HB + (size_t)idx * 8)); const f32x4 g0 = *(const f32x4*)(gf + c), g1 = *(const f32x4*)(gf + c + 4);
;         f32x4 v0 = (f32x4){bf_lo(q.x), bf_hi(q.x), bf_lo(q.y), bf_hi(q.y)}, v1 = (f32x4){bf_lo(q.z), bf_hi(q.z), bf_lo(q.w), bf_hi(q.w)};
;         v0 *= g0 * rs; v1 *= g1 * rs;
;         __builtin_nontemporal_store(v0, (f32x4*)(out + (size_t)idx * 8)); __builtin_nontemporal_store(v1, (f32x4*)(out + (size_t)idx * 8 + 4));
	global_store_dwordx4 v246, v[96:99], s[98:99] offset:528 nt
	v_mul_f32_e32 v234, v192, v210
	v_mul_f32_e32 v235, v193, v210
	v_mul_f32_e32 v236, v194, v210
	v_mul_f32_e32 v237, v195, v210
	v_mul_f32_e32 v238, v196, v210
	v_mul_f32_e32 v239, v197, v210
	v_mul_f32_e32 v240, v198, v210
	v_mul_f32_e32 v241, v199, v210
	v_mul_f32_e32 v92, v92, v234
	v_mul_f32_e32 v93, v93, v235
	v_mul_f32_e32 v94, v94, v236
	v_mul_f32_e32 v95, v95, v237
	v_mul_f32_e32 v88, v88, v238
	v_mul_f32_e32 v89, v89, v239
	v_mul_f32_e32 v90, v90, v240
	v_mul_f32_e32 v91, v91, v241
	v_mul_f32_e32 v234, v200, v210
	v_mul_f32_e32 v235, v201, v210
	v_mul_f32_e32 v236, v202, v210
	v_mul_f32_e32 v237, v203, v210
	v_mul_f32_e32 v238, v204, v210
	v_mul_f32_e32 v239, v205, v210
	v_mul_f32_e32 v240, v206, v210
	v_mul_f32_e32 v241, v207, v210
	v_mul_f32_e32 v84, v84, v234
	v_mul_f32_e32 v85, v85, v235
	v_mul_f32_e32 v86, v86, v236
	v_mul_f32_e32 v87, v87, v237
	v_mul_f32_e32 v80, v80, v238
	v_mul_f32_e32 v81, v81, v239
	v_mul_f32_e32 v82, v82, v240
	v_mul_f32_e32 v83, v83, v241
	v_add_u32_e32 v246, 0x20000, v250
	global_store_dwordx4 v246, v[92:95], s[98:99] nt
	global_store_dwordx4 v246, v[88:91], s[98:99] offset:16 nt
	global_store_dwordx4 v246, v[84:87], s[98:99] offset:512 nt
	global_store_dwordx4 v246, v[80:83], s[98:99] offset:528 nt
	v_mul_f32_e32 v234, v192, v211
	v_mul_f32_e32 v235, v193, v211
	v_mul_f32_e32 v236, v194, v211
	v_mul_f32_e32 v237, v195, v211
	v_mul_f32_e32 v238, v196, v211
	v_mul_f32_e32 v239, v197, v211
	v_mul_f32_e32 v240, v198, v211
	v_mul_f32_e32 v241, v199, v211
	v_mul_f32_e32 v76, v76, v234
	v_mul_f32_e32 v77, v77, v235
	v_mul_f32_e32 v78, v78, v236
	v_mul_f32_e32 v79, v79, v237
	v_mul_f32_e32 v72, v72, v238
	v_mul_f32_e32 v73, v73, v239
	v_mul_f32_e32 v74, v74, v240
	v_mul_f32_e32 v75, v75, v241
	v_mul_f32_e32 v234, v200, v211
	v_mul_f32_e32 v235, v201, v211
	v_mul_f32_e32 v236, v202, v211
	v_mul_f32_e32 v237, v203, v211
	v_mul_f32_e32 v238, v204, v211
	v_mul_f32_e32 v239, v205, v211
	v_mul_f32_e32 v240, v206, v211
	v_mul_f32_e32 v241, v207, v211
	v_mul_f32_e32 v68, v68, v234
	v_mul_f32_e32 v69, v69, v235
	v_mul_f32_e32 v70, v70, v236
	v_mul_f32_e32 v71, v71, v237
	v_mul_f32_e32 v64, v64, v238
	v_mul_f32_e32 v65, v65, v239
	v_mul_f32_e32 v66, v66, v240
	v_mul_f32_e32 v67, v67, v241
	v_add_u32_e32 v246, 0x30000, v250
	global_store_dwordx4 v246, v[76:79], s[98:99] nt
	global_store_dwordx4 v246, v[72:75], s[98:99] offset:16 nt
	global_store_dwordx4 v246, v[68:71], s[98:99] offset:512 nt
	global_store_dwordx4 v246, v[64:67], s[98:99] offset:528 nt
	v_mul_f32_e32 v234, v192, v212
	v_mul_f32_e32 v235, v193, v212
	v_mul_f32_e32 v236, v194, v212
	v_mul_f32_e32 v237, v195, v212
	v_mul_f32_e32 v238, v196, v212
	v_mul_f32_e32 v239, v197, v212
	v_mul_f32_e32 v240, v198, v212
	v_mul_f32_e32 v241, v199, v212
	v_mul_f32_e32 v60, v60, v234
	v_mul_f32_e32 v61, v61, v235
	v_mul_f32_e32 v62, v62, v236
	v_mul_f32_e32 v63, v63, v237
	v_mul_f32_e32 v56, v56, v238
	v_mul_f32_e32 v57, v57, v239
	v_mul_f32_e32 v58, v58, v240
	v_mul_f32_e32 v59, v59, v241
	v_mul_f32_e32 v234, v200, v212
	v_mul_f32_e32 v235, v201, v212
	v_mul_f32_e32 v236, v202, v212
	v_mul_f32_e32 v237, v203, v212
	v_mul_f32_e32 v238, v204, v212
	v_mul_f32_e32 v239, v205, v212
	v_mul_f32_e32 v240, v206, v212
	v_mul_f32_e32 v241, v207, v212
	v_mul_f32_e32 v52, v52, v234
	v_mul_f32_e32 v53, v53, v235
	v_mul_f32_e32 v54, v54, v236
	v_mul_f32_e32 v55, v55, v237
	v_mul_f32_e32 v48, v48, v238
	v_mul_f32_e32 v49, v49, v239
	v_mul_f32_e32 v50, v50, v240
	v_mul_f32_e32 v51, v51, v241
	v_add_u32_e32 v246, 0x80000, v250
	global_store_dwordx4 v246, v[60:63], s[98:99] nt
	global_store_dwordx4 v246, v[56:59], s[98:99] offset:16 nt
	global_store_dwordx4 v246, v[52:55], s[98:99] offset:512 nt
; __device__ __forceinline__ float bf_lo(unsigned w) { return __uint_as_float(w << 16); }
; __device__ __forceinline__ float bf_hi(unsigned w) { return __uint_as_float(w & 0xffff0000u); }
; __device__ __forceinline__ void final_phase(float* out, const bf16_t* HB, const float* ssq, const float* gf) {
;     ...
;         const float rs = rsqrtf(ssq[r] * (1.0f / DM) + RMS_EPS);
;         const u32x4 q = __builtin_nontemporal_load((const u32x4*)(HB + (size_t)idx * 8)); const f32x4 g0 = *(const f32x4*)(gf + c), g1 = *(const f32x4*)(gf + c + 4);
;         f32x4 v0 = (f32x4){bf_lo(q.x), bf_hi(q.x), bf_lo(q.y), bf_hi(q.y)}, v1 = (f32x4){bf_lo(q.z), bf_hi(q.z), bf_lo(q.w), bf_hi(q.w)};
;         v0 *= g0 * rs; v1 *= g1 * rs;
;         __builtin_nontemporal_store(v0, (f32x4*)(out + (size_t)idx * 8)); __builtin_nontemporal_store(v1, (f32x4*)(out + (size_t)idx * 8 + 4));
	global_store_dwordx4 v246, v[48:51], s[98:99] offset:528 nt
	v_mul_f32_e32 v234, v192, v213
	v_mul_f32_e32 v235, v193, v213
	v_mul_f32_e32 v236, v194, v213
	v_mul_f32_e32 v237, v195, v213
	v_mul_f32_e32 v238, v196, v213
	v_mul_f32_e32 v239, v197, v213
	v_mul_f32_e32 v240, v198, v213
	v_mul_f32_e32 v241, v199, v213
	v_mul_f32_e32 v44, v44, v234
	v_mul_f32_e32 v45, v45, v235
	v_mul_f32_e32 v46, v46, v236
	v_mul_f32_e32 v47, v47, v237
	v_mul_f32_e32 v40, v40, v238
	v_mul_f32_e32 v41, v41, v239
	v_mul_f32_e32 v42, v42, v240
	v_mul_f32_e32 v43, v43, v241
	v_mul_f32_e32 v234, v200, v213
	v_mul_f32_e32 v235, v201, v213
	v_mul_f32_e32 v236, v202, v213
	v_mul_f32_e32 v237, v203, v213
	v_mul_f32_e32 v238, v204, v213
	v_mul_f32_e32 v239, v205, v213
	v_mul_f32_e32 v240, v206, v213
	v_mul_f32_e32 v241, v207, v213
	v_mul_f32_e32 v36, v36, v234
	v_mul_f32_e32 v37, v37, v235
	v_mul_f32_e32 v38, v38, v236
	v_mul_f32_e32 v39, v39, v237
	v_mul_f32_e32 v32, v32, v238
	v_mul_f32_e32 v33, v33, v239
	v_mul_f32_e32 v34, v34, v240
	v_mul_f32_e32 v35, v35, v241
	v_add_u32_e32 v246, 0x90000, v250
	global_store_dwordx4 v246, v[44:47], s[98:99] nt
	global_store_dwordx4 v246, v[40:43], s[98:99] offset:16 nt
	global_store_dwordx4 v246, v[36:39], s[98:99] offset:512 nt
	global_store_dwordx4 v246, v[32:35], s[98:99] offset:528 nt
	v_mul_f32_e32 v234, v192, v214
	v_mul_f32_e32 v235, v193, v214
	v_mul_f32_e32 v236, v194, v214
	v_mul_f32_e32 v237, v195, v214
	v_mul_f32_e32 v238, v196, v214
	v_mul_f32_e32 v239, v197, v214
	v_mul_f32_e32 v240, v198, v214
	v_mul_f32_e32 v241, v199, v214
	v_mul_f32_e32 v28, v28, v234
	v_mul_f32_e32 v29, v29, v235
	v_mul_f32_e32 v30, v30, v236
	v_mul_f32_e32 v31, v31, v237
	v_mul_f32_e32 v24, v24, v238
	v_mul_f32_e32 v25, v25, v239
	v_mul_f32_e32 v26, v26, v240
	v_mul_f32_e32 v27, v27, v241
	v_mul_f32_e32 v234, v200, v214
	v_mul_f32_e32 v235, v201, v214
	v_mul_f32_e32 v236, v202, v214
	v_mul_f32_e32 v237, v203, v214
	v_mul_f32_e32 v238, v204, v214
	v_mul_f32_e32 v239, v205, v214
	v_mul_f32_e32 v240, v206, v214
	v_mul_f32_e32 v241, v207, v214
	v_mul_f32_e32 v20, v20, v234
	v_mul_f32_e32 v21, v21, v235
	v_mul_f32_e32 v22, v22, v236
	v_mul_f32_e32 v23, v23, v237
	v_mul_f32_e32 v16, v16, v238
	v_mul_f32_e32 v17, v17, v239
	v_mul_f32_e32 v18, v18, v240
	v_mul_f32_e32 v19, v19, v241
	v_add_u32_e32 v246, 0xa0000, v250
	global_store_dwordx4 v246, v[28:31], s[98:99] nt
	global_store_dwordx4 v246, v[24:27], s[98:99] offset:16 nt
	global_store_dwordx4 v246, v[20:23], s[98:99] offset:512 nt
	global_store_dwordx4 v246, v[16:19], s[98:99] offset:528 nt
	v_mul_f32_e32 v234, v192, v215
	v_mul_f32_e32 v235, v193, v215
	v_mul_f32_e32 v236, v194, v215
	v_mul_f32_e32 v237, v195, v215
	v_mul_f32_e32 v238, v196, v215
	v_mul_f32_e32 v239, v197, v215
	v_mul_f32_e32 v240, v198, v215
	v_mul_f32_e32 v241, v199, v215
	v_mul_f32_e32 v12, v12, v234
	v_mul_f32_e32 v13, v13, v235
	v_mul_f32_e32 v14, v14, v236
	v_mul_f32_e32 v15, v15, v237
	v_mul_f32_e32 v8, v8, v238
	v_mul_f32_e32 v9, v9, v239
	v_mul_f32_e32 v10, v10, v240
	v_mul_f32_e32 v11, v11, v241
	v_mul_f32_e32 v234, v200, v215
	v_mul_f32_e32 v235, v201, v215
	v_mul_f32_e32 v236, v202, v215
	v_mul_f32_e32 v237, v203, v215
	v_mul_f32_e32 v238, v204, v215
	v_mul_f32_e32 v239, v205, v215
	v_mul_f32_e32 v240, v206, v215
	v_mul_f32_e32 v241, v207, v215
	v_mul_f32_e32 v4, v4, v234
	v_mul_f32_e32 v5, v5, v235
	v_mul_f32_e32 v6, v6, v236
	v_mul_f32_e32 v7, v7, v237
	v_mul_f32_e32 v0, v0, v238
	v_mul_f32_e32 v1, v1, v239
	v_mul_f32_e32 v2, v2, v240
	v_mul_f32_e32 v3, v3, v241
	v_add_u32_e32 v246, 0xb0000, v250
	global_store_dwordx4 v246, v[12:15], s[98:99] nt
	global_store_dwordx4 v246, v[8:11], s[98:99] offset:16 nt
	global_store_dwordx4 v246, v[4:7], s[98:99] offset:512 nt
	global_store_dwordx4 v246, v[0:3], s[98:99] offset:528 nt
	s_branch .LBB0_1053

;     __device__ __forceinline__ void init(int M, int N, int lda, int K) { nM = M / BM; nN = N / BM; nwg = nM * nN; G = gridDim.x; c = blockIdx.x; asm volatile("" : "+s"(c), "+s"(nN));     atile = (size_t)BM * lda * 2; btile = (size_t)BM * K * 2; }
;     __device__ __forceinline__ void init(int K) { G = gridDim.x; c = blockIdx.x; asm volatile("" : "+s"(c)); btile = (size_t)BM * K * 2; }
; #define GRID_SYNC() grid_bar(bar, xcc, xst)
; __global__ void __launch_bounds__(512, 2) fwd_megakernel(Params p) {
;     ...
;     { StdOrder S; S.init(MTOK, 1024, 2816, 2816); fixup_local<0>(halo, p.ffn_conv_w + 3 * DFF, p.ffn_conv_b + DFF, ACT, DFF, S); EpiRes<true> E{HB, ssq + 3 * MTOK}; gemm_phase(lds, ACT, 2816, (const bf16_t*)(p.ws + WS_WDN1), 2816, S, E); }
;     GRID_SYNC();
;     final_phase(p.out, HB, ssq + 3 * MTOK, p.norm_final);
.LBB0_1086:
	s_cmp_eq_u32 s34, 0x100
	s_cbranch_scc1 .LBB0_1118
	s_waitcnt vmcnt(0) lgkmcnt(0)
	s_waitcnt lgkmcnt(0)
	s_barrier
	s_mov_b64 s[0:1], exec
	v_readlane_b32 s2, v252, 1
	v_readlane_b32 s36, v252, 6
	v_readlane_b32 s3, v252, 2
	v_readlane_b32 s42, v252, 12
	v_readlane_b32 s43, v252, 13
	s_and_b64 s[2:3], s[0:1], s[2:3]
	s_mov_b64 s[18:19], s[42:43]
	v_readlane_b32 s37, v252, 7
	v_readlane_b32 s38, v252, 8
	v_readlane_b32 s39, v252, 9
	v_readlane_b32 s40, v252, 10
	v_readlane_b32 s41, v252, 11
	v_readlane_b32 s44, v252, 14
	v_readlane_b32 s45, v252, 15
	v_readlane_b32 s46, v252, 16
	v_readlane_b32 s47, v252, 17
	v_readlane_b32 s48, v252, 18
	v_readlane_b32 s49, v252, 19
	v_readlane_b32 s50, v252, 20
	v_readlane_b32 s51, v252, 21
	s_mov_b64 exec, s[2:3]
	s_cbranch_execz .LBB0_1115
	s_add_i32 s2, 0, 0x20000
	v_mov_b32_e32 v0, s2
	s_waitcnt vmcnt(0) expcnt(0) lgkmcnt(0)
	ds_read_b32 v1, v0
	s_add_i32 s2, 0, 0x20004
	v_mov_b32_e32 v0, s2
	ds_read_b32 v0, v0
	s_waitcnt lgkmcnt(1)
	v_cmp_ne_u32_e32 vcc, 0, v1
	s_cbranch_vccnz .LBB0_1093
	s_add_u32 s4, s62, 0x1000
	s_addc_u32 s5, s63, 0
	s_add_u32 s6, s62, 0x1100
	s_addc_u32 s7, s63, 0
	s_add_u32 s8, s62, 0x1200
	s_addc_u32 s9, s63, 0
	s_add_u32 s10, s62, 0x1300
	s_addc_u32 s11, s63, 0
	v_mov_b32_e32 v16, 0
	s_branch .LBB0_1090

; #define LAS __attribute__((address_space(3)))
; __global__ void __launch_bounds__(512, 2) fwd_megakernel(Params p) {
;     extern __shared__ __attribute__((aligned(16))) unsigned char smem[];
;     LAS unsigned char* lds = (LAS unsigned char*)smem;
	.amdhsa_kernel _Z14fwd_megakernel6Params
		.amdhsa_group_segment_fixed_size 0
		.amdhsa_private_segment_fixed_size 0
		.amdhsa_kernarg_size 432
		.amdhsa_user_sgpr_count 2
		.amdhsa_user_sgpr_dispatch_ptr 0
		.amdhsa_user_sgpr_queue_ptr 0
		.amdhsa_user_sgpr_kernarg_segment_ptr 1
		.amdhsa_user_sgpr_dispatch_id 0
		.amdhsa_user_sgpr_kernarg_preload_length 0
		.amdhsa_user_sgpr_kernarg_preload_offset 0
		.amdhsa_user_sgpr_private_segment_size 0
		.amdhsa_uses_dynamic_stack 0
		.amdhsa_enable_private_segment 0
		.amdhsa_system_sgpr_workgroup_id_x 1
		.amdhsa_system_sgpr_workgroup_id_y 0
		.amdhsa_system_sgpr_workgroup_id_z 0
		.amdhsa_system_sgpr_workgroup_info 0
		.amdhsa_system_vgpr_workitem_id 2
		.amdhsa_next_free_vgpr 253
		.amdhsa_next_free_sgpr 102
		.amdhsa_accum_offset 256
		.amdhsa_reserve_vcc 1
		.amdhsa_float_round_mode_32 0
		.amdhsa_float_round_mode_16_64 0
		.amdhsa_float_denorm_mode_32 3
		.amdhsa_float_denorm_mode_16_64 3
		.amdhsa_dx10_clamp 1
		.amdhsa_ieee_mode 1
		.amdhsa_fp16_overflow 0
		.amdhsa_tg_split 0
		.amdhsa_exception_fp_ieee_invalid_op 0
		.amdhsa_exception_fp_denorm_src 0
		.amdhsa_exception_fp_ieee_div_zero 0
		.amdhsa_exception_fp_ieee_overflow 0
		.amdhsa_exception_fp_ieee_underflow 0
		.amdhsa_exception_fp_ieee_inexact 0
		.amdhsa_exception_int_div_zero 0
	.end_amdhsa_kernel

; #define LAS __attribute__((address_space(3)))
; __global__ void __launch_bounds__(512, 2) fwd_megakernel(Params p) {
;     extern __shared__ __attribute__((aligned(16))) unsigned char smem[];
;     LAS unsigned char* lds = (LAS unsigned char*)smem;
amdhsa.kernels:
  - .agpr_count:     0
    .args:
      - .offset:         0
        .size:           176
        .value_kind:     by_value
      - .offset:         176
        .size:           4
        .value_kind:     hidden_block_count_x
      - .offset:         180
        .size:           4
        .value_kind:     hidden_block_count_y
      - .offset:         184
        .size:           4
        .value_kind:     hidden_block_count_z
      - .offset:         188
        .size:           2
        .value_kind:     hidden_group_size_x
      - .offset:         190
        .size:           2
        .value_kind:     hidden_group_size_y
      - .offset:         192
        .size:           2
        .value_kind:     hidden_group_size_z
      - .offset:         194
        .size:           2
        .value_kind:     hidden_remainder_x
      - .offset:         196
        .size:           2
        .value_kind:     hidden_remainder_y
      - .offset:         198
        .size:           2
        .value_kind:     hidden_remainder_z
      - .offset:         216
        .size:           8
        .value_kind:     hidden_global_offset_x
      - .offset:         224
        .size:           8
        .value_kind:     hidden_global_offset_y
      - .offset:         232
        .size:           8
        .value_kind:     hidden_global_offset_z
      - .offset:         240
        .size:           2
        .value_kind:     hidden_grid_dims
      - .offset:         264
        .size:           8
        .value_kind:     hidden_multigrid_sync_arg
      - .offset:         296
        .size:           4
        .value_kind:     hidden_dynamic_lds_size
    .group_segment_fixed_size: 0
    .kernarg_segment_align: 8
    .kernarg_segment_size: 432
    .language:       OpenCL C
    .language_version:
      - 2
      - 0
    .max_flat_workgroup_size: 512
    .name:           _Z14fwd_megakernel6Params
    .private_segment_fixed_size: 0
    .sgpr_count:     108
    .sgpr_spill_count: 56
    .symbol:         _Z14fwd_megakernel6Params.kd
    .uniform_work_group_size: 1
    .uses_dynamic_stack: false
    .vgpr_count:     253
    .vgpr_spill_count: 0
    .wavefront_size: 64
